# barriers after layer-1 mixers and layer-1 FFN-b up wait only on the XCD's own arrival counter (data flows within one XCD; guarded by a placement flag)
# baseline (speedup 1.0000x reference)
_Z3fwd4Args:
	s_load_dwordx8 s[20:27], s[0:1], 0x80
	v_writelane_b32 v252, s2, 0
	s_mov_b32 s2, 0
	s_waitcnt lgkmcnt(0)
	s_cmp_lg_u32 s26, 0
	s_cselect_b64 s[56:57], -1, 0
	s_cmp_eq_u32 s26, 0
	s_cbranch_scc1 .LBB0_7
	v_and_b32_e32 v1, 0x3ff, v0
	v_cmp_gt_u32_e32 vcc, 32, v1
	s_and_saveexec_b64 s[4:5], vcc
	v_lshl_add_u32 v2, v1, 2, 0
	v_add_u32_e32 v2, 0x20000, v2
	v_mov_b32_e32 v3, 0
	ds_write_b32 v2, v3
	s_or_b64 exec, exec, s[4:5]
	s_waitcnt lgkmcnt(0)
	s_barrier
	s_getreg_b32 s2, hwreg(HW_REG_XCC_ID, 0, 4)
	s_and_b32 s2, s2, 15
	v_cmp_eq_u32_e32 vcc, 0, v1
	s_and_saveexec_b64 s[4:5], vcc
	s_cbranch_execz .LBB0_6
	s_mov_b64 s[6:7], exec
	v_mbcnt_lo_u32_b32 v1, s6, 0
	v_mbcnt_hi_u32_b32 v1, s7, v1
	v_cmp_eq_u32_e32 vcc, 0, v1
	s_and_b64 s[8:9], exec, vcc
	s_mov_b64 exec, s[8:9]
	s_cbranch_execz .LBB0_6
	s_lshl_b32 s3, s2, 8
	s_bcnt1_i32_b64 s6, s[6:7]
	v_mov_b32_e32 v1, s3
	v_mov_b32_e32 v2, s6
	global_atomic_add v1, v2, s[22:23] offset:1024
	v_readlane_b32 s7, v252, 0
	v_mov_b32_e32 v3, 0
	s_nop 2
	s_and_b32 s7, s7, 7
	s_cmp_eq_u32 s7, s2
	s_cbranch_scc1 .Lmy_place_ok
	global_atomic_add v3, v2, s[22:23] offset:516
.Lmy_place_ok:
.LBB0_6:
	s_or_b64 exec, exec, s[4:5]
	s_add_i32 s58, 0, 0x20020
	s_branch .LBB0_8

.LBB0_1206:
	v_readlane_b32 s2, v254, 3
	v_readlane_b32 s3, v254, 4
	v_cvt_f32_u32_e32 v1, v2
	v_sub_u32_e32 v4, 0, v2
	v_rcp_iflag_f32_e32 v1, v1
	s_nop 1
	global_atomic_add v3, v33, v179, s[2:3] sc0
	global_load_dword v7, v33, s[22:23] offset:516 sc1
	v_mul_f32_e32 v1, 0x4f7ffffe, v1
	v_cvt_u32_f32_e32 v1, v1
	v_mul_lo_u32 v4, v4, v1
	v_mul_hi_u32 v4, v1, v4
	v_add_u32_e32 v1, v1, v4
	s_waitcnt vmcnt(0)
	v_mul_hi_u32 v1, v3, v1
	v_mul_lo_u32 v4, v1, v2
	v_sub_u32_e32 v4, v3, v4
	v_add_u32_e32 v5, 1, v1
	v_cmp_ge_u32_e32 vcc, v4, v2
	v_add_u32_e32 v3, 1, v3
	s_nop 0
	v_cndmask_b32_e32 v1, v1, v5, vcc
	v_sub_u32_e32 v5, v4, v2
	v_cndmask_b32_e32 v4, v4, v5, vcc
	v_add_u32_e32 v5, 1, v1
	v_cmp_ge_u32_e32 vcc, v4, v2
	s_nop 1
	v_cndmask_b32_e32 v1, v1, v5, vcc
	v_mul_lo_u32 v4, v2, v1
	v_add_u32_e32 v2, v4, v2
	v_cmp_ne_u32_e32 vcc, v3, v2
	s_waitcnt lgkmcnt(0)
	v_add_u32_e32 v6, 1, v1
	v_mul_lo_u32 v6, v6, v0
	v_readlane_b32 s2, v254, 7
	v_readlane_b32 s3, v254, 8
	s_mov_b32 s0, 0
	v_readfirstlane_b32 s31, v7
	s_lshr_b32 s30, s33, 1
	s_cmp_eq_u32 s30, 16
	s_cselect_b32 s34, 1, 0
	s_cmp_eq_u32 s30, 19
	s_cselect_b32 s35, 1, 0
	s_or_b32 s34, s34, s35
	s_cmp_eq_u32 s31, 0
	s_cselect_b32 s35, 1, 0
	s_and_b32 s34, s34, s35
	s_cmp_lg_u32 s34, 0
	s_cbranch_scc1 .Lmy_bar_local
	s_cbranch_vccnz .Lmy_bar_poll
	buffer_wbl2 sc1
	s_waitcnt vmcnt(0)
	global_atomic_add v33, v179, s[2:3]

.Lmy_bar_local:
	s_mov_b64 s[34:35], s[2:3]
	v_readlane_b32 s2, v254, 3
	v_readlane_b32 s3, v254, 4
	v_mov_b32_e32 v6, v2
	s_cbranch_vccnz .Lmy_bar_lpoll
	global_atomic_add v33, v179, s[34:35]
.Lmy_bar_lpoll:
	s_nop 4
	s_branch .Lmy_bar_loop
